# on top of keep6: two more quads of the F1 running mix kept in 16 KiB extra static LDS (8 of 16 quads on-chip)
# baseline (speedup 1.0000x reference)
.LBB0_880:
	v_lshlrev_b32_e32 v252, 4, v216
	v_add_u32_e32 v252, 0x21000, v252
	s_mov_b32 s98, s7
	s_lshl_b32 s22, s7, 11
	s_ashr_i32 s23, s22, 31
	s_cmp_lg_u32 s7, 0
	s_cselect_b64 s[24:25], -1, 0
	s_lshl_b32 s17, s6, 8
	s_lshl_b64 s[22:23], s[22:23], 1
	v_add_u32_e32 v210, s17, v217
	s_add_u32 s22, s39, s22
	v_ashrrev_i32_e32 v211, 31, v210
	s_addc_u32 s23, s40, s23
	v_lshl_or_b32 v208, s49, 8, v222
	v_lshlrev_b64 v[64:65], 14, v[210:211]
	v_lshl_add_u64 v[64:65], s[22:23], 0, v[64:65]
	v_ashrrev_i32_e32 v209, 31, v208
	v_lshl_add_u64 v[64:65], v[208:209], 1, v[64:65]
	global_load_dwordx4 v[188:191], v[64:65], off
	v_lshlrev_b64 v[66:67], 12, v[210:211]
	v_lshl_add_u64 v[66:67], s[10:11], 0, v[66:67]
	s_cmp_eq_u32 s7, 0
	v_lshl_add_u64 v[212:213], v[208:209], 1, v[66:67]
	s_cbranch_scc1 .LBB0_882

.LBB0_892:
	v_or_b32_e32 v66, 48, v210
	v_ashrrev_i32_e32 v67, 31, v66
	v_lshlrev_b64 v[64:65], 14, v[66:67]
	v_lshl_add_u64 v[64:65], s[22:23], 0, v[64:65]
	v_lshl_add_u64 v[64:65], v[208:209], 1, v[64:65]
	global_load_dwordx4 v[164:167], v[64:65], off
	v_lshlrev_b64 v[66:67], 12, v[66:67]
	v_lshl_add_u64 v[66:67], s[10:11], 0, v[66:67]
	s_and_b64 vcc, exec, s[6:7]
	v_lshl_add_u64 v[214:215], v[208:209], 1, v[66:67]
	s_cbranch_vccnz .LBB0_894
	ds_read_b128 v[68:71], v252
.LBB0_894:
	global_load_dwordx4 v[160:163], v[64:65], off offset:256
	s_and_b64 vcc, exec, s[6:7]
	s_cbranch_vccnz .LBB0_896
	ds_read_b128 v[64:67], v252 offset:8192
.LBB0_896:
	s_waitcnt vmcnt(0)
	s_waitcnt lgkmcnt(0)
	v_lshlrev_b32_e32 v214, 16, v188
	v_and_b32_e32 v215, 0xffff0000, v188
	v_lshlrev_b32_e32 v188, 16, v189
	v_and_b32_e32 v189, 0xffff0000, v189
	v_pk_mul_f32 v[158:159], v[158:159], v[188:189]
	v_lshlrev_b32_e32 v188, 16, v190
	v_and_b32_e32 v189, 0xffff0000, v190
	v_pk_mul_f32 v[152:153], v[152:153], v[188:189]
	v_lshlrev_b32_e32 v188, 16, v191
	v_and_b32_e32 v189, 0xffff0000, v191
	v_pk_mul_f32 v[156:157], v[156:157], v[214:215]
	s_and_b64 vcc, exec, s[6:7]
	v_pk_mul_f32 v[154:155], v[154:155], v[188:189]
	s_cbranch_vccnz .LBB0_898
	v_lshlrev_b32_e32 v188, 16, v228
	v_and_b32_e32 v189, 0xffff0000, v228
	v_lshlrev_b32_e32 v190, 16, v229
	v_and_b32_e32 v191, 0xffff0000, v229
	v_lshlrev_b32_e32 v214, 16, v230
	v_and_b32_e32 v215, 0xffff0000, v230
	v_lshlrev_b32_e32 v226, 16, v231
	v_and_b32_e32 v227, 0xffff0000, v231
	v_pk_add_f32 v[158:159], v[158:159], v[190:191]
	v_pk_add_f32 v[156:157], v[156:157], v[188:189]
	v_pk_add_f32 v[154:155], v[154:155], v[226:227]
	v_pk_add_f32 v[152:153], v[152:153], v[214:215]

.LBB0_910:
	v_add_u32_e32 v96, s17, v221
	v_cvt_pk_bf16_f32 v92, v92, v93
	v_cvt_pk_bf16_f32 v93, v94, v95
	v_cvt_pk_bf16_f32 v95, v86, v87
	v_lshlrev_b32_e32 v86, 16, v160
	v_and_b32_e32 v87, 0xffff0000, v160
	v_ashrrev_i32_e32 v97, 31, v96
	v_pk_mul_f32 v[76:77], v[76:77], v[86:87]
	v_lshlrev_b32_e32 v86, 16, v161
	v_and_b32_e32 v87, 0xffff0000, v161
	v_cvt_pk_bf16_f32 v94, v84, v85
	v_lshlrev_b64 v[84:85], 12, v[96:97]
	v_pk_mul_f32 v[78:79], v[78:79], v[86:87]
	v_lshlrev_b32_e32 v86, 16, v162
	v_and_b32_e32 v87, 0xffff0000, v162
	v_lshl_add_u64 v[84:85], s[10:11], 0, v[84:85]
	v_pk_mul_f32 v[72:73], v[72:73], v[86:87]
	v_lshlrev_b32_e32 v86, 16, v163
	v_and_b32_e32 v87, 0xffff0000, v163
	v_lshl_add_u64 v[84:85], v[208:209], 1, v[84:85]
	s_and_b64 vcc, exec, s[6:7]
	v_pk_mul_f32 v[74:75], v[74:75], v[86:87]
	ds_write_b128 v252, v[92:95]
	s_cmp_eq_u32 s98, 3
	s_cbranch_scc0 .Lf1k_102
	global_store_dwordx4 v[84:85], v[92:95], off
.Lf1k_102:
	s_cbranch_vccnz .LBB0_912
	v_lshlrev_b32_e32 v86, 16, v64
	v_and_b32_e32 v87, 0xffff0000, v64
	v_lshlrev_b32_e32 v92, 16, v65
	v_and_b32_e32 v93, 0xffff0000, v65
	v_lshlrev_b32_e32 v94, 16, v66
	v_and_b32_e32 v95, 0xffff0000, v66
	v_lshlrev_b32_e32 v96, 16, v67
	v_and_b32_e32 v97, 0xffff0000, v67
	v_pk_add_f32 v[78:79], v[78:79], v[92:93]
	v_pk_add_f32 v[76:77], v[76:77], v[86:87]
	v_pk_add_f32 v[74:75], v[74:75], v[96:97]
	v_pk_add_f32 v[72:73], v[72:73], v[94:95]
.LBB0_912:
	v_cvt_pk_bf16_f32 v76, v76, v77
	v_cvt_pk_bf16_f32 v77, v78, v79
	v_cvt_pk_bf16_f32 v78, v72, v73
	v_cvt_pk_bf16_f32 v79, v74, v75
	ds_write_b128 v252, v[76:79] offset:8192
	s_cmp_eq_u32 s98, 3
	s_cbranch_scc0 .Lf1k_103
	global_store_dwordx4 v[84:85], v[76:79], off offset:256
.Lf1k_103:
	v_add_u32_e32 v72, 0x80, v210
	v_ashrrev_i32_e32 v73, 31, v72
	v_lshlrev_b64 v[74:75], 14, v[72:73]
	v_lshl_add_u64 v[74:75], s[22:23], 0, v[74:75]
	v_lshl_add_u64 v[74:75], v[208:209], 1, v[74:75]
	global_load_dwordx4 v[116:119], v[74:75], off
	v_lshlrev_b64 v[76:77], 12, v[72:73]
	v_lshl_add_u64 v[76:77], s[10:11], 0, v[76:77]
	s_and_b64 vcc, exec, s[6:7]
	v_lshl_add_u64 v[124:125], v[208:209], 1, v[76:77]
	s_cbranch_vccnz .LBB0_914
	global_load_dwordx4 v[132:135], v[124:125], off

	.amdhsa_kernel _Z6mk_fwd4Args
		.amdhsa_group_segment_fixed_size 16384
		.amdhsa_private_segment_fixed_size 0
		.amdhsa_kernarg_size 448
		.amdhsa_user_sgpr_count 2
		.amdhsa_user_sgpr_dispatch_ptr 0
		.amdhsa_user_sgpr_queue_ptr 0
		.amdhsa_user_sgpr_kernarg_segment_ptr 1
		.amdhsa_user_sgpr_dispatch_id 0
		.amdhsa_user_sgpr_kernarg_preload_length 0
		.amdhsa_user_sgpr_kernarg_preload_offset 0
		.amdhsa_user_sgpr_private_segment_size 0
		.amdhsa_uses_dynamic_stack 0
		.amdhsa_enable_private_segment 0
		.amdhsa_system_sgpr_workgroup_id_x 1
		.amdhsa_system_sgpr_workgroup_id_y 0
		.amdhsa_system_sgpr_workgroup_id_z 0
		.amdhsa_system_sgpr_workgroup_info 0
		.amdhsa_system_vgpr_workitem_id 2
		.amdhsa_next_free_vgpr 256
		.amdhsa_next_free_sgpr 102
		.amdhsa_accum_offset 256
		.amdhsa_reserve_vcc 1
		.amdhsa_float_round_mode_32 0
		.amdhsa_float_round_mode_16_64 0
		.amdhsa_float_denorm_mode_32 3
		.amdhsa_float_denorm_mode_16_64 3
		.amdhsa_dx10_clamp 1
		.amdhsa_ieee_mode 1
		.amdhsa_fp16_overflow 0
		.amdhsa_tg_split 0
		.amdhsa_exception_fp_ieee_invalid_op 0
		.amdhsa_exception_fp_denorm_src 0
		.amdhsa_exception_fp_ieee_div_zero 0
		.amdhsa_exception_fp_ieee_overflow 0
		.amdhsa_exception_fp_ieee_underflow 0
		.amdhsa_exception_fp_ieee_inexact 0
		.amdhsa_exception_int_div_zero 0
	.end_amdhsa_kernel

amdhsa.kernels:
  - .agpr_count:     0
    .args:
      - .offset:         0
        .size:           192
        .value_kind:     by_value
      - .offset:         192
        .size:           4
        .value_kind:     hidden_block_count_x
      - .offset:         196
        .size:           4
        .value_kind:     hidden_block_count_y
      - .offset:         200
        .size:           4
        .value_kind:     hidden_block_count_z
      - .offset:         204
        .size:           2
        .value_kind:     hidden_group_size_x
      - .offset:         206
        .size:           2
        .value_kind:     hidden_group_size_y
      - .offset:         208
        .size:           2
        .value_kind:     hidden_group_size_z
      - .offset:         210
        .size:           2
        .value_kind:     hidden_remainder_x
      - .offset:         212
        .size:           2
        .value_kind:     hidden_remainder_y
      - .offset:         214
        .size:           2
        .value_kind:     hidden_remainder_z
      - .offset:         232
        .size:           8
        .value_kind:     hidden_global_offset_x
      - .offset:         240
        .size:           8
        .value_kind:     hidden_global_offset_y
      - .offset:         248
        .size:           8
        .value_kind:     hidden_global_offset_z
      - .offset:         256
        .size:           2
        .value_kind:     hidden_grid_dims
      - .offset:         280
        .size:           8
        .value_kind:     hidden_multigrid_sync_arg
      - .offset:         312
        .size:           4
        .value_kind:     hidden_dynamic_lds_size
    .group_segment_fixed_size: 16384
    .kernarg_segment_align: 8
    .kernarg_segment_size: 448
    .language:       OpenCL C
    .language_version:
      - 2
      - 0
    .max_flat_workgroup_size: 512
    .name:           _Z6mk_fwd4Args
    .private_segment_fixed_size: 0
    .sgpr_count:     108
    .sgpr_spill_count: 37
    .symbol:         _Z6mk_fwd4Args.kd
    .uniform_work_group_size: 1
    .uses_dynamic_stack: false
    .vgpr_count:     256
    .vgpr_spill_count: 0
    .wavefront_size: 64
